# FoX item prologue: pruning-bound loads issued together up front (moves at the old sites)
# baseline (speedup 1.0000x reference)
.LBB0_307:
	s_ashr_i32 s1, s2, 31
	s_lshr_b32 s1, s1, 27
	v_mov_b32_e32 v104, v177
	s_add_i32 s1, s2, s1
	s_ashr_i32 s3, s1, 5
	v_ashrrev_i32_e32 v4, 6, v104
	s_andn2_b32 s1, s1, 31
	v_readfirstlane_b32 s0, v4
	s_sub_i32 s6, 64, s3
	s_sub_i32 s7, s2, s1
	s_mov_b64 s[68:69], s[50:51]
	s_ashr_i32 s50, s7, 3
	s_lshl_b32 s18, s6, 7
	s_lshl_b32 s0, s0, 5
	s_add_i32 s52, s0, s18
	s_mul_i32 s0, s50, 0x2ce0c00
	s_ashr_i32 s1, s0, 31
	s_lshl_b64 s[0:1], s[0:1], 1
	s_add_u32 s2, s56, s0
	v_and_b32_e32 v5, 31, v104
	s_addc_u32 s3, s57, s1
	v_or_b32_e32 v102, s52, v5
	v_mov_b64_e32 v[0:1], s[2:3]
	v_mad_i64_i32 v[0:1], s[0:1], v102, s13, v[0:1]
	s_lshl_b32 s0, s7, 6
	s_and_b32 s0, s0, 0x1c0
	v_bfe_u32 v3, v104, 5, 1
	s_lshl_b32 s92, s0, 1
	s_mov_b32 s93, s17
	v_readlane_b32 s8, v245, 36
	v_lshl_add_u64 v[0:1], v[0:1], 0, s[92:93]
	v_lshlrev_b32_e32 v178, 4, v3
	s_mul_i32 s1, s7, 0x410
	v_readlane_b32 s10, v245, 38
	v_and_b32_e32 v2, 63, v104
	v_lshl_add_u64 v[0:1], v[0:1], 0, v[178:179]
	s_mul_hi_i32 s0, s7, 0x410
	v_readlane_b32 s11, v245, 39
	s_add_u32 s10, s10, s1
	global_load_dwordx4 v[64:67], v[0:1], off
	global_load_dwordx4 v[68:71], v[0:1], off offset:32
	global_load_dwordx4 v[72:75], v[0:1], off offset:64
	global_load_dwordx4 v[76:79], v[0:1], off offset:96
	s_addc_u32 s11, s11, s0
	v_lshlrev_b32_e32 v0, 3, v2
	global_load_dword v1, v0, s[10:11] offset:4
	s_nop 0
	global_load_dword v0, v0, s[10:11] offset:516
	s_movk_i32 s0, 0x82
	v_readlane_b32 s9, v245, 37
	s_mul_i32 s82, s7, 0x8200
	s_add_u32 s80, s60, s82
	s_addc_u32 s81, s61, 0
	v_or_b32_e32 v166, 0x80, v2
	v_min_u32_e32 v166, 0x81, v166
	v_lshlrev_b32_e32 v166, 3, v166
	global_load_dword v157, v166, s[10:11] offset:4
	s_lshl_b32 s82, s6, 4
	s_add_u32 s70, s10, s82
	s_addc_u32 s71, s11, 0
	global_load_dword v158, v179, s[70:71]
	global_load_dword v159, v179, s[70:71] offset:8
	s_lshl_b32 s82, s6, 9
	s_add_u32 s72, s80, s82
	s_addc_u32 s73, s81, 0
	global_load_dword v160, v179, s[72:73]
	v_add_u32_e32 v167, 0x81, v2
	v_lshlrev_b32_e32 v167, 8, v167
	global_load_dword v161, v167, s[80:81] offset:252
	v_add_u32_e32 v167, 0x41, v2
	v_lshlrev_b32_e32 v167, 8, v167
	global_load_dword v162, v167, s[80:81] offset:252
	v_add_u32_e32 v167, 1, v2
	v_lshlrev_b32_e32 v167, 8, v167
	global_load_dword v163, v167, s[80:81] offset:252
	s_ashr_i32 s82, s52, 5
	s_and_b32 s82, s82, -2
	s_lshl_b32 s82, s82, 2
	s_add_u32 s74, s10, s82
	s_addc_u32 s75, s11, 0
	global_load_dword v164, v179, s[74:75]
	s_lshl_b32 s82, s52, 2
	s_add_u32 s76, s80, s82
	s_addc_u32 s77, s81, 0
	global_load_dword v165, v179, s[76:77]
	s_waitcnt vmcnt(0)
	v_max3_f32 v0, v1, 0, v0
	v_or_b32_e32 v1, 0x80, v2
	v_cmp_gt_u32_e32 vcc, s0, v1
	s_and_saveexec_b64 s[0:1], vcc
	s_cbranch_execz .LBB0_309
	v_lshlrev_b32_e32 v1, 3, v1
	v_mov_b32_e32 v1, v157
	v_max_f32_e32 v0, v0, v0
	s_waitcnt vmcnt(0)
	v_max_f32_e32 v1, v1, v1
	v_max_f32_e32 v0, v0, v1
.LBB0_309:
	s_or_b64 exec, exec, s[0:1]
	v_and_b32_e32 v1, 64, v224
	v_add_u32_e32 v1, 64, v1
	v_xor_b32_e32 v6, 32, v224
	v_cmp_lt_i32_e32 vcc, v6, v1
	s_mul_hi_i32 s0, s7, 0x8200
	s_mul_i32 s7, s7, 0x8200
	v_cndmask_b32_e32 v6, v224, v6, vcc
	v_lshlrev_b32_e32 v103, 2, v6
	ds_bpermute_b32 v6, v103, v0
	v_max_f32_e32 v0, v0, v0
	s_lshl_b32 s51, s6, 1
	s_add_u32 s8, s60, s7
	s_addc_u32 s9, s61, s0
	s_waitcnt lgkmcnt(0)
	v_max_f32_e32 v6, v6, v6
	v_max_f32_e32 v0, v0, v6
	v_xor_b32_e32 v6, 16, v224
	v_cmp_lt_i32_e32 vcc, v6, v1
	s_lshl_b32 s16, s6, 2
	s_or_b32 s44, s51, 1
	v_cndmask_b32_e32 v6, v224, v6, vcc
	v_lshlrev_b32_e32 v6, 2, v6
	ds_bpermute_b32 v6, v6, v0
	s_lshl_b64 s[0:1], s[16:17], 2
	s_add_u32 s0, s10, s0
	s_addc_u32 s1, s11, s1
	s_lshl_b32 s16, s44, 1
	s_waitcnt lgkmcnt(0)
	v_max_f32_e32 v6, v6, v6
	v_max_f32_e32 v0, v0, v6
	v_xor_b32_e32 v6, 8, v224
	v_cmp_lt_i32_e32 vcc, v6, v1
	s_mov_b32 s19, s17
	s_mov_b64 s[6:7], 0
	v_cndmask_b32_e32 v6, v224, v6, vcc
	v_lshlrev_b32_e32 v6, 2, v6
	ds_bpermute_b32 v6, v6, v0
	s_waitcnt lgkmcnt(0)
	v_max_f32_e32 v6, v6, v6
	v_max_f32_e32 v0, v0, v6
	v_xor_b32_e32 v6, 4, v224
	v_cmp_lt_i32_e32 vcc, v6, v1
	s_nop 1
	v_cndmask_b32_e32 v6, v224, v6, vcc
	v_lshlrev_b32_e32 v6, 2, v6
	ds_bpermute_b32 v6, v6, v0
	s_waitcnt lgkmcnt(0)
	v_max_f32_e32 v6, v6, v6
	v_max_f32_e32 v0, v0, v6
	v_xor_b32_e32 v6, 2, v224
	v_cmp_lt_i32_e32 vcc, v6, v1
	s_nop 1
	v_cndmask_b32_e32 v6, v224, v6, vcc
	v_lshlrev_b32_e32 v6, 2, v6
	ds_bpermute_b32 v6, v6, v0
	s_waitcnt lgkmcnt(0)
	v_max_f32_e32 v6, v6, v6
	v_max_f32_e32 v0, v0, v6
	v_xor_b32_e32 v6, 1, v224
	v_cmp_lt_i32_e32 vcc, v6, v1
	s_nop 1
	v_cndmask_b32_e32 v1, v224, v6, vcc
	v_lshlrev_b32_e32 v1, 2, v1
	ds_bpermute_b32 v1, v1, v0
	s_waitcnt lgkmcnt(0)
	v_max_f32_e32 v1, v1, v1
	v_max_f32_e32 v0, v0, v1
	v_mov_b32_e32 v1, v158
	s_lshl_b64 s[0:1], s[16:17], 2
	s_add_u32 s0, s10, s0
	s_addc_u32 s1, s11, s1
	v_mov_b32_e32 v6, v159
	s_waitcnt vmcnt(1)
	v_max_f32_e32 v1, v1, v1
	s_waitcnt vmcnt(0)
	v_max_f32_e32 v6, v6, v6
	v_max_f32_e32 v1, v1, v6
	v_mul_f32_e32 v1, v0, v1
	v_cmp_gt_f32_e32 vcc, s53, v1
	v_mul_f32_e32 v6, 0x4f800000, v1
	s_nop 0
	v_cndmask_b32_e32 v1, v1, v6, vcc
	v_sqrt_f32_e32 v6, v1
	s_nop 0
	v_add_u32_e32 v7, -1, v6
	v_fma_f32 v8, -v7, v6, v1
	v_cmp_ge_f32_e64 s[0:1], 0, v8
	v_add_u32_e32 v8, 1, v6
	s_nop 0
	v_cndmask_b32_e64 v7, v6, v7, s[0:1]
	v_fma_f32 v6, -v8, v6, v1
	v_cmp_lt_f32_e64 s[0:1], 0, v6
	s_nop 1
	v_cndmask_b32_e64 v6, v7, v8, s[0:1]
	s_lshl_b64 s[0:1], s[18:19], 2
	v_mul_f32_e32 v7, 0x37800000, v6
	s_add_u32 s0, s8, s0
	v_cndmask_b32_e32 v6, v6, v7, vcc
	v_cmp_class_f32_e32 vcc, v1, v222
	s_addc_u32 s1, s9, s1
	s_nop 0
	v_cndmask_b32_e32 v1, v6, v1, vcc
	v_mov_b32_e32 v6, v160
	v_fmamk_f32 v1, v1, 0x3eb8adac, v223
	s_mov_b64 s[0:1], 0
	s_waitcnt vmcnt(0)
	v_mul_f32_e32 v7, 0x3fb8aa3b, v6
	v_add_u32_e32 v6, 0x81, v2
	v_cmp_ge_u32_e32 vcc, s44, v6
	v_lshlrev_b32_e32 v6, 8, v6
	s_and_saveexec_b64 s[18:19], vcc
	s_cbranch_execz .LBB0_311
	v_mov_b32_e32 v8, v161
	s_waitcnt vmcnt(0)
	v_fmamk_f32 v8, v8, 0xbfb8aa3b, v7
	v_add_f32_e32 v8, v1, v8
	v_cmp_le_f32_e64 s[0:1], 0, v8
	s_and_b64 s[0:1], s[0:1], exec
.LBB0_311:
	s_or_b64 exec, exec, s[18:19]
	v_cndmask_b32_e64 v8, 0, 1, s[0:1]
	v_cmp_ne_u32_e64 s[0:1], 0, v8
	v_add_u32_e32 v8, 0x41, v2
	v_cmp_ge_u32_e64 s[24:25], s44, v8
	v_lshlrev_b32_e32 v8, 8, v8
	s_and_saveexec_b64 s[22:23], s[24:25]
	s_cbranch_execz .LBB0_313
	v_mov_b32_e32 v9, v162
	s_waitcnt vmcnt(0)
	v_fmamk_f32 v9, v9, 0xbfb8aa3b, v7
	v_add_f32_e32 v9, v1, v9
	v_cmp_le_f32_e64 s[18:19], 0, v9
	s_and_b64 s[6:7], s[18:19], exec
.LBB0_313:
	s_or_b64 exec, exec, s[22:23]
	v_add_u32_e32 v9, 1, v2
	v_cndmask_b32_e64 v10, 0, 1, s[6:7]
	v_cmp_ne_u32_e64 s[18:19], 0, v10
	v_cmp_ge_u32_e64 s[26:27], s51, v2
	s_mov_b64 s[6:7], 0
	v_lshlrev_b32_e32 v9, 8, v9
	s_mov_b64 s[22:23], 0
	s_and_saveexec_b64 s[30:31], s[26:27]
	s_cbranch_execz .LBB0_315
	v_mov_b32_e32 v10, v163
	s_waitcnt vmcnt(0)
	v_fmac_f32_e32 v7, 0xbfb8aa3b, v10
	v_add_f32_e32 v1, v1, v7
	v_cmp_le_f32_e64 s[22:23], 0, v1
	s_and_b64 s[22:23], s[22:23], exec
.LBB0_315:
	s_or_b64 exec, exec, s[30:31]
	s_ashr_i32 s16, s52, 5
	s_and_b32 s30, s16, -2
	s_ashr_i32 s31, s30, 31
	s_lshl_b64 s[30:31], s[30:31], 2
	s_add_u32 s10, s10, s30
	v_cndmask_b32_e64 v1, 0, 1, s[22:23]
	s_addc_u32 s11, s11, s31
	v_cmp_ne_u32_e64 s[22:23], 0, v1
	v_mov_b32_e32 v1, v164
	s_waitcnt vmcnt(0)
	v_mul_f32_e32 v0, v0, v1
	v_cmp_gt_f32_e64 s[30:31], s53, v0
	v_mul_f32_e32 v1, 0x4f800000, v0
	s_ashr_i32 s53, s52, 31
	v_cndmask_b32_e64 v0, v0, v1, s[30:31]
	v_sqrt_f32_e32 v1, v0
	s_lshl_b64 s[10:11], s[52:53], 2
	s_add_u32 s10, s8, s10
	s_addc_u32 s11, s9, s11
	v_add_u32_e32 v7, -1, v1
	v_fma_f32 v10, -v7, v1, v0
	v_cmp_ge_f32_e64 s[34:35], 0, v10
	v_add_u32_e32 v10, 1, v1
	s_nop 0
	v_cndmask_b32_e64 v7, v1, v7, s[34:35]
	v_fma_f32 v1, -v10, v1, v0
	v_cmp_lt_f32_e64 s[34:35], 0, v1
	s_nop 1
	v_cndmask_b32_e64 v1, v7, v10, s[34:35]
	v_mul_f32_e32 v7, 0x37800000, v1
	v_cndmask_b32_e64 v1, v1, v7, s[30:31]
	v_cmp_class_f32_e64 s[30:31], v0, v222
	s_nop 1
	v_cndmask_b32_e64 v0, v1, v0, s[30:31]
	v_mov_b32_e32 v1, v165
	v_fmamk_f32 v0, v0, 0x3eb8adac, v223
	s_waitcnt vmcnt(0)
	v_mul_f32_e32 v1, 0x3fb8aa3b, v1
	s_and_saveexec_b64 s[10:11], vcc
	s_cbranch_execz .LBB0_317
	v_mov_b32_e32 v6, v161
	s_waitcnt vmcnt(0)
	v_fmamk_f32 v6, v6, 0xbfb8aa3b, v1
	v_add_f32_e32 v6, v0, v6
	v_cmp_le_f32_e32 vcc, 0, v6
	s_and_b64 s[6:7], vcc, exec
.LBB0_317:
	s_or_b64 exec, exec, s[10:11]
	v_cndmask_b32_e64 v6, 0, 1, s[6:7]
	v_cmp_ne_u32_e32 vcc, 0, v6
	s_mov_b64 s[6:7], 0
	s_mov_b64 s[30:31], 0
	s_and_saveexec_b64 s[10:11], s[24:25]
	s_cbranch_execz .LBB0_319
	v_mov_b32_e32 v6, v162
	s_waitcnt vmcnt(0)
	v_fmamk_f32 v6, v6, 0xbfb8aa3b, v1
	v_add_f32_e32 v6, v0, v6
	v_cmp_le_f32_e64 s[24:25], 0, v6
	s_and_b64 s[30:31], s[24:25], exec
.LBB0_319:
	s_or_b64 exec, exec, s[10:11]
	v_cndmask_b32_e64 v6, 0, 1, s[30:31]
	v_cmp_ne_u32_e64 s[24:25], 0, v6
	s_and_saveexec_b64 s[10:11], s[26:27]
	s_mov_b32 s53, 0xf800000
	s_cbranch_execz .LBB0_321
	v_mov_b32_e32 v6, v163
	s_waitcnt vmcnt(0)
	v_fmac_f32_e32 v1, 0xbfb8aa3b, v6
	v_add_f32_e32 v0, v0, v1
	v_cmp_le_f32_e64 s[26:27], 0, v0
	s_and_b64 s[6:7], s[26:27], exec
